# P3 scan: the two scan items of a workgroup staggered by half a chunk step (one extra s_barrier before vb1's first step, one after vb0's last)
# baseline (speedup 1.0000x reference)
; DEV void gdn_scan_item(const Params& p, int item, unsigned char* lds) {
;     int tid = threadIdx.x & 255; asm volatile("" : "+v"(tid)); const int lane = tid & 63, w = tid >> 6, fr = lane & 15, fq = lane >> 4;
;     const int s = item & 7, bh = item >> 3;
;     const int b = bh >> 3, h = bh & 7;
;     bf16_t* ST = (bf16_t*)lds;
;     bf16_t* VT = ST + 16 * QS;
;     const char* bW = (const char*)((const bf16_t*)(p.ws + WS_GW) + (size_t)bh * 32 * 8192);
;     const char* bQ = (const char*)((const bf16_t*)(p.ws + WS_GQ) + (size_t)bh * 32 * 8192);
;     const char* bK = (const char*)((const bf16_t*)(p.ws + WS_GKT) + (size_t)bh * 32 * 8192);
;     const char* bA = (const char*)((const bf16_t*)(p.ws + WS_GA) + (size_t)bh * 32 * 4096);
;     const char* bU = (const char*)((const float*)(p.ws + WS_GU) + (size_t)bh * 32 * 8192);
;     const float* gE = (const float*)(p.ws + WS_GE) + bh * 32;
;     float* obuf = (float*)(p.ws + WS_O);
;     f32x4 S0 = {0.f, 0.f, 0.f, 0.f}, S1 = {0.f, 0.f, 0.f, 0.f};
;     for (int i = tid; i < 16 * QS / 2; i += 256) ((unsigned*)ST)[i] = 0u;
;     const float egv = gE[lane & 31];
;     const unsigned offWQ = (unsigned)(((w * 16 + fr) * 32 + fq * 8) * 2), offA = offWQ;
;     const unsigned offK = (unsigned)(((w * 32 + fr) * 32 + fq * 8) * 2), offU = (unsigned)((((s * 4 + w) * 16 + fq) * 16 + fr) * 4);
;     ScanEarly E0, E1, E2; ScanLate L0, L1;
;     ...
;     LOAD_E(E0, 0); LOAD_L(L0, 0); LOAD_E(E1, 1);
;     __syncthreads();
; __global__ void __launch_bounds__(512) hymba_fwd(Params p) {
;     ...
;             if (G == 256) {
;                 const int x = bid & 7, j = bid >> 3;
;                 gdn_scan_item(p, ((x * 4 + (j >> 2)) << 3) | ((j & 3) << 1) | vb, vlds);
.LBB0_887:
	s_or_b64 exec, exec, s[4:5]
	s_lshl_b32 s4, s2, 2
	s_and_b32 s4, s4, 28
	s_ashr_i32 s5, s2, 5
	s_add_i32 s4, s4, s5
	s_lshr_b32 s5, s2, 2
	s_lshl_b32 s4, s4, 3
	s_and_b32 s5, s5, 6
	s_or_b32 s4, s4, s5
	s_or_b32 s35, s71, s4
	s_ashr_i32 s4, s35, 3
	s_ashr_i32 s5, s4, 31
	s_and_b32 s34, s35, 7
	s_lshl_b64 s[18:19], s[4:5], 18
	s_lshl_b64 s[16:17], s[4:5], 19
	s_waitcnt lgkmcnt(0)
	s_add_u32 s38, s8, s16
	s_addc_u32 s39, s9, s17
	s_add_u32 s22, s38, 0xdb08000
	s_addc_u32 s23, s39, 0
	s_add_u32 s24, s38, 0xeb08000
	s_addc_u32 s25, s39, 0
	s_add_u32 s10, s38, 0xfb08000
	s_addc_u32 s11, s39, 0
	s_add_u32 s6, s8, s18
	s_addc_u32 s7, s9, s19
	s_add_u32 s12, s6, 0x10b08000
	s_addc_u32 s13, s7, 0
	s_lshl_b64 s[20:21], s[4:5], 20
	s_add_u32 s26, s8, s20
	s_addc_u32 s27, s9, s21
	s_lshl_b32 s6, s4, 5
	s_ashr_i32 s7, s6, 31
	s_lshl_b64 s[6:7], s[6:7], 2
	s_add_u32 s30, s8, s6
	v_and_b32_e32 v1, 31, v90
	v_ashrrev_i32_e32 v4, 6, v90
	s_addc_u32 s31, s9, s7
	v_lshlrev_b32_e32 v180, 2, v1
	v_mov_b32_e32 v181, 0
	v_and_b32_e32 v178, 15, v90
	v_bfe_u32 v91, v90, 4, 2
	s_add_u32 s6, s8, 0x13309000
	v_lshl_add_u64 v[2:3], s[30:31], 0, v[180:181]
	s_mov_b32 s30, 0x13308000
	v_lshlrev_b32_e32 v1, 4, v4
	s_addc_u32 s7, s9, 0
	v_add_co_u32_e32 v10, vcc, s30, v2
	v_or_b32_e32 v2, v1, v178
	v_lshlrev_b32_e32 v93, 4, v91
	s_lshl_b32 s40, s34, 6
	v_lshl_or_b32 v180, v2, 6, v93
	v_add_u32_e32 v2, s40, v1
	v_lshlrev_b32_e32 v176, 5, v4
	v_or_b32_e32 v13, v2, v91
	v_lshlrev_b32_e32 v92, 2, v178
	v_or_b32_e32 v12, v176, v178
	v_lshl_or_b32 v98, v13, 6, v92
	v_mov_b32_e32 v99, v181
	v_lshl_or_b32 v184, v12, 6, v93
	v_lshl_add_u64 v[12:13], s[26:27], 0, v[98:99]
	s_mov_b64 s[36:37], 0x11308000
	v_addc_co_u32_e32 v11, vcc, 0, v3, vcc
	v_lshl_add_u64 v[14:15], v[12:13], 0, s[36:37]
	s_mov_b32 s36, 0x11308000
	v_add_co_u32_e32 v12, vcc, s36, v12
	s_add_u32 s36, s38, 0xdb0c000
	s_addc_u32 s37, s39, 0
	s_add_u32 s38, s38, 0xeb0c000
	s_addc_u32 s39, s39, 0
	v_add_u32_e32 v182, 0x1000, v180
	v_addc_co_u32_e32 v13, vcc, 0, v13, vcc
	v_or_b32_e32 v16, 0x100, v98
	v_or_b32_e32 v17, 0x200, v98
	s_add_u32 s26, s26, 0x11310000
	v_add_u32_e32 v188, 0x2000, v184
	global_load_dwordx4 v[6:9], v182, s[22:23]
	global_load_dwordx4 v[2:5], v182, s[24:25]
	v_add_u32_e32 v94, 0x2000, v180
	v_add_u32_e32 v96, 0x3000, v180
	v_or_b32_e32 v22, 0x300, v98
	s_addc_u32 s27, s27, 0
	global_load_dword v177, v[10:11], off
	global_load_dword v193, v[12:13], off
	global_load_dword v238, v[14:15], off offset:256
	global_load_dword v239, v[14:15], off offset:512
	global_load_dword v154, v16, s[26:27]
	global_load_dword v155, v17, s[26:27]
	global_load_dword v156, v22, s[26:27]
	global_load_dword v240, v[14:15], off offset:768
	global_load_dwordx4 v[18:21], v180, s[22:23]
	global_load_dwordx4 v[86:89], v180, s[12:13]
	global_load_dwordx4 v[70:73], v184, s[10:11]
	global_load_dwordx4 v[66:69], v184, s[10:11] offset:1024
	v_add_u32_e32 v186, 0x2400, v184
	global_load_dwordx4 v[82:85], v188, s[10:11]
	global_load_dwordx4 v[78:81], v186, s[10:11]
	global_load_dwordx4 v[38:41], v180, s[24:25]
	global_load_dwordx4 v[30:33], v180, s[36:37]
	global_load_dwordx4 v[34:37], v180, s[38:39]
	global_load_dwordx4 v[46:49], v182, s[36:37]
	global_load_dwordx4 v[50:53], v182, s[38:39]
	global_load_dwordx4 v[14:17], v94, s[24:25]
	global_load_dwordx4 v[42:45], v94, s[36:37]
	global_load_dwordx4 v[74:77], v182, s[12:13]
	global_load_dwordx4 v[54:57], v94, s[38:39]
	global_load_dwordx4 v[10:13], v96, s[24:25]
	global_load_dwordx4 v[58:61], v96, s[36:37]
	global_load_dwordx4 v[26:29], v94, s[22:23]
	global_load_dwordx4 v[62:65], v96, s[38:39]
	global_load_dwordx4 v[22:25], v96, s[22:23]
	global_load_dword v157, v98, s[26:27]
	s_movk_i32 s22, 0x110
	v_mov_b32_e32 v101, s70
	v_mad_u32_u24 v102, v178, s22, v101
	s_movk_i32 s22, 0x90
	v_mad_u32_u24 v101, v178, s22, v101
	s_lshl_b32 s22, s35, 5
	s_and_b32 s24, s22, 0xfffff800
	s_lshl_b32 s22, s4, 7
	s_and_b32 s22, s22, 0x380
	s_lshl_b32 s23, s22, 2
	s_add_u32 s25, s6, s23
	s_addc_u32 s27, s7, 0
	s_lshl_b32 s23, s34, 4
	v_lshlrev_b32_e32 v100, 3, v91
	v_and_b32_e32 v90, 0xffffffc0, v90
	s_add_u32 s26, s25, s40
	v_mov_b32_e32 v183, v181
	v_mov_b32_e32 v95, v181
	v_mov_b32_e32 v97, v181
	v_mov_b32_e32 v185, v181
	v_mov_b32_e32 v189, v181
	v_mov_b32_e32 v187, v181
	v_add_u32_e32 v237, v102, v93
	v_lshlrev_b32_e32 v179, 2, v91
	v_add_u32_e32 v235, v101, v93
	v_add3_u32 v234, v102, v90, v100
	s_addc_u32 s27, s27, 0
	v_mov_b32_e32 v93, v181
	v_add_u32_e32 v90, s24, v1
	s_movk_i32 s30, 0x2000
	s_movk_i32 s31, 0x3000
	v_add3_u32 v236, v101, v176, v100
	v_lshl_add_u64 v[190:191], s[26:27], 0, v[92:93]
	v_or_b32_e32 v192, v90, v179
	v_lshl_add_u64 v[194:195], s[20:21], 0, v[98:99]
	v_lshl_add_u64 v[196:197], s[16:17], 0, v[180:181]
	v_lshl_add_u64 v[198:199], s[16:17], 0, v[182:183]
	v_lshl_add_u64 v[200:201], s[16:17], 0, v[94:95]
	v_lshl_add_u64 v[202:203], s[16:17], 0, v[96:97]
	v_lshl_add_u64 v[204:205], s[18:19], 0, v[180:181]
	v_lshl_add_u64 v[206:207], s[18:19], 0, v[182:183]
	v_lshl_add_u64 v[208:209], s[16:17], 0, v[184:185]
	v_lshl_add_u64 v[210:211], s[16:17], 0, v[188:189]
	v_lshl_add_u64 v[212:213], s[16:17], 0, v[186:187]
	s_mov_b32 s62, -6
	s_mov_b32 s25, 0xdb10000
	s_mov_b32 s26, 0xeb10000
	s_mov_b32 s27, 0x11318000
	s_mov_b32 s34, 0x10b0a000
	s_mov_b32 s35, 0xfb0c000
	s_mov_b32 s36, 0xdb14000
	s_mov_b32 s37, 0xeb14000
	s_mov_b32 s38, 0x11320000
	s_mov_b32 s39, 0x10b0c000
	s_mov_b32 s40, 0xfb10000
	s_mov_b32 s41, 0xdb18000
	s_mov_b32 s42, 0xeb18000
	s_mov_b32 s43, 0x11328000
	s_mov_b32 s44, 0x10b0e000
	s_mov_b32 s45, 0xfb14000
	s_mov_b32 s46, 0xdb1c000
	s_mov_b32 s47, 0xeb1c000
	s_mov_b32 s48, 0x11330000
	s_mov_b32 s49, 0x10b10000
	s_mov_b32 s50, 0xfb18000
	s_mov_b32 s51, 0xdb20000
	s_mov_b32 s52, 0xeb20000
	s_mov_b32 s53, 0x11338000
	s_mov_b32 s54, 0x10b12000
	s_mov_b32 s55, 0xfb1c000
	s_mov_b32 s56, 0xdb24000
	s_mov_b32 s57, 0xeb24000
	s_mov_b32 s58, 0x11340000
	s_mov_b32 s59, 0x10b14000
	s_mov_b32 s60, 0xfb20000
	s_mov_b64 s[16:17], 0x30000
	s_mov_b64 s[18:19], 0x18000
	s_mov_b64 s[20:21], 0xc000
	v_mov_b32_e32 v94, v181
	v_mov_b32_e32 v96, v181
	v_mov_b32_e32 v90, v181
	v_mov_b32_e32 v91, v181
	v_mov_b32_e32 v92, v181
	s_waitcnt vmcnt(63) expcnt(7) lgkmcnt(15)
	s_barrier
	s_cmp_eq_u32 s71, 0
	s_cbranch_scc1 .Lscan_stag0
	s_barrier
.Lscan_stag0:
.LBB0_888:
	ds_read_b128 v[246:249], v237
	v_lshl_add_u64 v[214:215], s[8:9], 0, v[196:197]
	v_add_co_u32_e32 v98, vcc, s25, v214
	v_lshl_add_u64 v[216:217], s[8:9], 0, v[198:199]
	s_nop 0
	v_addc_co_u32_e32 v99, vcc, 0, v215, vcc
	v_add_co_u32_e32 v102, vcc, s26, v214
	v_lshl_add_u64 v[218:219], s[8:9], 0, v[200:201]
	s_nop 0
	v_addc_co_u32_e32 v103, vcc, 0, v215, vcc
	v_add_co_u32_e32 v106, vcc, s25, v216
	v_lshl_add_u64 v[220:221], s[8:9], 0, v[202:203]
	s_nop 0
	v_addc_co_u32_e32 v107, vcc, 0, v217, vcc
	v_add_co_u32_e32 v110, vcc, s26, v216
	v_lshl_add_u64 v[222:223], s[8:9], 0, v[194:195]
	s_nop 0
	v_addc_co_u32_e32 v111, vcc, 0, v217, vcc
	v_add_co_u32_e32 v114, vcc, s25, v218
	v_lshl_add_u64 v[224:225], s[8:9], 0, v[204:205]
	s_nop 0
	v_addc_co_u32_e32 v115, vcc, 0, v219, vcc
	v_add_co_u32_e32 v118, vcc, s26, v218
	global_load_dwordx4 v[98:101], v[98:99], off
	s_nop 0
	v_addc_co_u32_e32 v119, vcc, 0, v219, vcc
	v_add_co_u32_e32 v122, vcc, s25, v220
	global_load_dwordx4 v[102:105], v[102:103], off
	s_nop 0
	v_addc_co_u32_e32 v123, vcc, 0, v221, vcc
	v_add_co_u32_e32 v126, vcc, s26, v220
	global_load_dwordx4 v[106:109], v[106:107], off
	s_nop 0
	v_addc_co_u32_e32 v127, vcc, 0, v221, vcc
	v_add_co_u32_e32 v130, vcc, s27, v222
	global_load_dwordx4 v[110:113], v[110:111], off
	s_nop 0
	v_addc_co_u32_e32 v131, vcc, 0, v223, vcc
	global_load_dwordx4 v[114:117], v[114:115], off
	v_lshl_add_u64 v[226:227], s[8:9], 0, v[206:207]
	global_load_dwordx4 v[118:121], v[118:119], off
	v_lshl_add_u64 v[228:229], s[8:9], 0, v[208:209]
	global_load_dwordx4 v[122:125], v[122:123], off
	v_lshl_add_u64 v[230:231], s[8:9], 0, v[210:211]
	global_load_dwordx4 v[126:129], v[126:127], off
	s_nop 0
	global_load_dword v241, v[130:131], off
	global_load_dword v242, v[130:131], off offset:256
	global_load_dword v243, v[130:131], off offset:512
	global_load_dword v244, v[130:131], off offset:768
	v_add_co_u32_e32 v130, vcc, s34, v224
	v_lshl_add_u64 v[232:233], s[8:9], 0, v[212:213]
	s_nop 0
	v_addc_co_u32_e32 v131, vcc, 0, v225, vcc
	v_add_co_u32_e32 v134, vcc, s34, v226
	global_load_dwordx4 v[130:133], v[130:131], off
	s_nop 0
	v_addc_co_u32_e32 v135, vcc, 0, v227, vcc
	v_add_co_u32_e32 v146, vcc, s35, v228
	global_load_dwordx4 v[134:137], v[134:135], off
	s_nop 0
	v_addc_co_u32_e32 v147, vcc, 0, v229, vcc
	v_add_co_u32_e32 v142, vcc, s35, v230
	global_load_dwordx4 v[138:141], v[146:147], off
	s_nop 0
	v_addc_co_u32_e32 v143, vcc, 0, v231, vcc
	global_load_dwordx4 v[142:145], v[142:143], off
	s_nop 0
	global_load_dwordx4 v[146:149], v[146:147], off offset:1024

	s_waitcnt vmcnt(37) lgkmcnt(0)
	v_mfma_f32_16x16x32_bf16 v[18:21], v[18:21], v[246:249], 0
	v_add_co_u32_e32 v150, vcc, s35, v232
	s_add_i32 s61, s62, 6
	s_waitcnt vmcnt(31)
	v_mfma_f32_16x16x32_bf16 v[38:41], v[38:41], v[246:249], 0
	ds_read_b128 v[246:249], v237 offset:64
	v_addc_co_u32_e32 v151, vcc, 0, v233, vcc
	s_waitcnt lgkmcnt(0)
	v_mfma_f32_16x16x32_bf16 v[6:9], v[6:9], v[246:249], v[18:21]
	global_load_dwordx4 v[150:153], v[150:151], off
	s_nop 1
	ds_read_b128 v[18:21], v237 offset:128
	s_add_i32 s65, s62, 7
	v_mfma_f32_16x16x32_bf16 v[2:5], v[2:5], v[246:249], v[38:41]
	v_readlane_b32 s64, v177, s61
	v_readlane_b32 s66, v177, s65
	s_add_i32 s63, s62, 8
	s_waitcnt vmcnt(27) lgkmcnt(0)
	v_mfma_f32_16x16x32_bf16 v[2:5], v[14:17], v[18:21], v[2:5]
	ds_read_b128 v[14:17], v237 offset:192
	v_lshl_add_u64 v[194:195], v[194:195], 0, s[16:17]
	v_lshl_add_u64 v[196:197], v[196:197], 0, s[18:19]
	s_waitcnt vmcnt(21)
	v_mfma_f32_16x16x32_bf16 v[6:9], v[26:29], v[18:21], v[6:9]
	v_mul_f32_e64 v20, v92, s64
	v_mul_f32_e64 v21, v93, s64
	v_pk_mul_f32 v[18:19], v[90:91], s[64:65] op_sel_hi:[1,0]
	v_lshl_add_u64 v[198:199], v[198:199], 0, s[18:19]
	s_waitcnt vmcnt(19) lgkmcnt(0)
	v_mfma_f32_16x16x32_bf16 v[6:9], v[22:25], v[14:17], v[6:9]
	v_lshl_add_u64 v[200:201], v[200:201], 0, s[18:19]
	v_lshl_add_u64 v[202:203], v[202:203], 0, s[18:19]
	v_lshl_add_u64 v[204:205], v[204:205], 0, s[20:21]
	v_mfma_f32_16x16x32_bf16 v[2:5], v[10:13], v[14:17], v[2:5]
	v_mul_f32_e64 v16, v96, s64
	v_mul_f32_e64 v17, v97, s64
	s_nop 1
	v_sub_f32_e32 v9, v240, v9
	v_sub_f32_e32 v8, v239, v8
	v_sub_f32_e32 v7, v238, v7
	v_sub_f32_e32 v6, v193, v6
	v_cvt_pk_bf16_f32 v6, v6, v7
	v_cvt_pk_bf16_f32 v7, v8, v9
	ds_write_b64 v236, v[6:7] offset:4352
	s_waitcnt lgkmcnt(0)
	s_barrier
	ds_read_b128 v[6:9], v235 offset:4352
	ds_read_b128 v[10:13], v235 offset:4416
	v_pk_mul_f32 v[14:15], v[94:95], s[64:65] op_sel_hi:[1,0]
	s_waitcnt lgkmcnt(1)
	v_mfma_f32_16x16x32_bf16 v[2:5], v[86:89], v[6:9], v[2:5]
	v_ashrrev_i32_e32 v193, 31, v192
	s_add_i32 s64, s62, 9
	s_add_i32 s65, s62, 10
	v_mfma_f32_16x16x32_bf16 v[14:17], v[70:73], v[6:9], v[14:17]
	v_readlane_b32 s64, v177, s64
	s_add_i32 s62, s62, 11
	v_readlane_b32 s62, v177, s62
	v_mfma_f32_16x16x32_bf16 v[6:9], v[66:69], v[6:9], v[18:21]
	v_lshl_add_u64 v[206:207], v[206:207], 0, s[20:21]
	v_lshl_add_u64 v[208:209], v[208:209], 0, s[18:19]
	v_lshl_add_u64 v[210:211], v[210:211], 0, s[18:19]
	s_waitcnt lgkmcnt(0)
	v_mfma_f32_16x16x32_bf16 v[90:93], v[82:85], v[10:13], v[14:17]
	v_lshl_add_u64 v[212:213], v[212:213], 0, s[18:19]
	s_cmp_lt_u32 s61, 24
	v_mfma_f32_16x16x32_bf16 v[94:97], v[78:81], v[10:13], v[6:9]
	v_mfma_f32_16x16x32_bf16 v[2:5], v[74:77], v[10:13], v[2:5]
	s_nop 3
	v_cvt_pk_bf16_f32 v6, v90, v91
	v_cvt_pk_bf16_f32 v7, v92, v93
	s_nop 0
	v_cvt_pk_bf16_f32 v8, v94, v95
	v_cvt_pk_bf16_f32 v9, v96, v97
	ds_write2_b64 v234, v[6:7], v[8:9] offset1:4
	v_lshlrev_b64 v[6:7], 12, v[192:193]
	v_lshl_add_u64 v[6:7], v[190:191], 0, v[6:7]
	v_add_co_u32_e32 v8, vcc, s30, v6
	global_store_dword v[6:7], v2, off
	s_nop 0
	v_addc_co_u32_e32 v9, vcc, 0, v7, vcc
	v_add_co_u32_e32 v2, vcc, s31, v6
	global_store_dword v[8:9], v3, off offset:-4096
	global_store_dword v[8:9], v4, off
	v_addc_co_u32_e32 v3, vcc, 0, v7, vcc
	global_store_dword v[2:3], v5, off
	v_add_co_u32_e32 v2, vcc, s36, v214
	s_waitcnt lgkmcnt(0)
	s_barrier
	ds_read_b128 v[246:249], v237
	s_nop 0
	v_addc_co_u32_e32 v3, vcc, 0, v215, vcc
	v_add_co_u32_e32 v6, vcc, s37, v214
	global_load_dwordx4 v[2:5], v[2:3], off
	s_nop 0
	v_addc_co_u32_e32 v7, vcc, 0, v215, vcc
	v_add_co_u32_e32 v10, vcc, s36, v216
	global_load_dwordx4 v[6:9], v[6:7], off
	s_nop 0
	v_addc_co_u32_e32 v11, vcc, 0, v217, vcc
	v_add_co_u32_e32 v14, vcc, s37, v216
	global_load_dwordx4 v[10:13], v[10:11], off
	s_nop 0
	v_addc_co_u32_e32 v15, vcc, 0, v217, vcc
	v_add_co_u32_e32 v18, vcc, s36, v218
	global_load_dwordx4 v[14:17], v[14:15], off
	s_nop 0
	v_addc_co_u32_e32 v19, vcc, 0, v219, vcc
	v_add_co_u32_e32 v22, vcc, s37, v218
	global_load_dwordx4 v[18:21], v[18:19], off
	s_nop 0
	v_addc_co_u32_e32 v23, vcc, 0, v219, vcc
	v_add_co_u32_e32 v26, vcc, s36, v220
	global_load_dwordx4 v[22:25], v[22:23], off
	s_nop 0
	v_addc_co_u32_e32 v27, vcc, 0, v221, vcc
	v_add_co_u32_e32 v38, vcc, s37, v220
	global_load_dwordx4 v[26:29], v[26:27], off
	s_nop 0
	v_addc_co_u32_e32 v39, vcc, 0, v221, vcc
	v_add_co_u32_e32 v66, vcc, s38, v222
	global_load_dwordx4 v[38:41], v[38:39], off
	s_nop 0
	v_addc_co_u32_e32 v67, vcc, 0, v223, vcc
	global_load_dword v193, v[66:67], off
	global_load_dword v238, v[66:67], off offset:256
	global_load_dword v239, v[66:67], off offset:512
	global_load_dword v240, v[66:67], off offset:768
	v_add_co_u32_e32 v66, vcc, s39, v224
	s_nop 1
	v_addc_co_u32_e32 v67, vcc, 0, v225, vcc
	v_add_co_u32_e32 v70, vcc, s39, v226
	global_load_dwordx4 v[66:69], v[66:67], off
	s_nop 0
	v_addc_co_u32_e32 v71, vcc, 0, v227, vcc
	v_add_co_u32_e32 v82, vcc, s40, v228
	global_load_dwordx4 v[74:77], v[70:71], off
	s_nop 0
	v_addc_co_u32_e32 v83, vcc, 0, v229, vcc
	v_add_co_u32_e32 v78, vcc, s40, v230
	global_load_dwordx4 v[70:73], v[82:83], off
	s_nop 0
	v_addc_co_u32_e32 v79, vcc, 0, v231, vcc
	global_load_dwordx4 v[78:81], v[78:79], off
	s_nop 0
	global_load_dwordx4 v[82:85], v[82:83], off offset:1024

	s_waitcnt lgkmcnt(0)
	v_mfma_f32_16x16x32_bf16 v[30:33], v[30:33], v[246:249], 0
	v_add_co_u32_e32 v86, vcc, s40, v232
	v_mfma_f32_16x16x32_bf16 v[34:37], v[34:37], v[246:249], 0
	ds_read_b128 v[246:249], v237 offset:64
	v_addc_co_u32_e32 v87, vcc, 0, v233, vcc
	s_waitcnt lgkmcnt(0)
	v_mfma_f32_16x16x32_bf16 v[30:33], v[46:49], v[246:249], v[30:33]
	ds_read_b128 v[46:49], v237 offset:128
	global_load_dwordx4 v[86:89], v[86:87], off
	s_waitcnt lgkmcnt(0)
	v_mfma_f32_16x16x32_bf16 v[30:33], v[42:45], v[46:49], v[30:33]
	ds_read_b128 v[42:45], v237 offset:192
	v_mfma_f32_16x16x32_bf16 v[34:37], v[50:53], v[246:249], v[34:37]
	v_mul_f32_e64 v52, v96, s66
	v_mul_f32_e64 v53, v97, s66
	v_pk_mul_f32 v[50:51], v[94:95], s[66:67] op_sel_hi:[1,0]
	s_waitcnt lgkmcnt(0)
	v_mfma_f32_16x16x32_bf16 v[30:33], v[58:61], v[42:45], v[30:33]
	v_mfma_f32_16x16x32_bf16 v[34:37], v[54:57], v[46:49], v[34:37]
	v_mul_f32_e64 v48, v92, s66
	v_mul_f32_e64 v49, v93, s66
	s_nop 4
	v_sub_f32_e32 v33, v156, v33
	v_sub_f32_e32 v32, v155, v32
	v_sub_f32_e32 v31, v154, v31
	s_waitcnt vmcnt(40)
	v_sub_f32_e32 v30, v157, v30
	v_cvt_pk_bf16_f32 v30, v30, v31
	v_cvt_pk_bf16_f32 v31, v32, v33
	ds_write_b64 v236, v[30:31] offset:4352
	s_waitcnt lgkmcnt(0)
	s_barrier
	v_mfma_f32_16x16x32_bf16 v[34:37], v[62:65], v[42:45], v[34:37]
	ds_read_b128 v[30:33], v235 offset:4352
	ds_read_b128 v[42:45], v235 offset:4416
	v_pk_mul_f32 v[46:47], v[90:91], s[66:67] op_sel_hi:[1,0]
	v_readlane_b32 s66, v177, s63
	s_waitcnt vmcnt(27) lgkmcnt(1)
	v_mfma_f32_16x16x32_bf16 v[34:37], v[130:133], v[30:33], v[34:37]
	s_waitcnt vmcnt(25)
	v_mfma_f32_16x16x32_bf16 v[46:49], v[138:141], v[30:33], v[46:49]
	s_waitcnt vmcnt(23)
	v_mfma_f32_16x16x32_bf16 v[30:33], v[146:149], v[30:33], v[50:53]
	s_waitcnt lgkmcnt(0)
	v_mfma_f32_16x16x32_bf16 v[90:93], v[142:145], v[42:45], v[46:49]
	s_waitcnt vmcnt(22)
	v_mfma_f32_16x16x32_bf16 v[94:97], v[150:153], v[42:45], v[30:33]
	v_mfma_f32_16x16x32_bf16 v[34:37], v[134:137], v[42:45], v[34:37]
	s_nop 4
	v_cvt_pk_bf16_f32 v30, v90, v91
	v_cvt_pk_bf16_f32 v31, v92, v93
	v_cvt_pk_bf16_f32 v32, v94, v95
	v_cvt_pk_bf16_f32 v33, v96, v97
	ds_write2_b64 v234, v[30:31], v[32:33] offset1:4
	v_add_u32_e32 v30, 64, v192
	v_ashrrev_i32_e32 v31, 31, v30
	v_lshlrev_b64 v[30:31], 12, v[30:31]
	v_lshl_add_u64 v[30:31], v[190:191], 0, v[30:31]
	v_add_co_u32_e32 v32, vcc, s30, v30
	global_store_dword v[30:31], v34, off
	s_nop 0
	v_addc_co_u32_e32 v33, vcc, 0, v31, vcc
	v_add_co_u32_e32 v30, vcc, s31, v30
	global_store_dword v[32:33], v35, off offset:-4096
	global_store_dword v[32:33], v36, off
	v_addc_co_u32_e32 v31, vcc, 0, v31, vcc
	global_store_dword v[30:31], v37, off
	v_add_co_u32_e32 v30, vcc, s41, v214
	s_waitcnt lgkmcnt(0)
	s_barrier
	ds_read_b128 v[154:157], v237
	s_nop 0
	v_addc_co_u32_e32 v31, vcc, 0, v215, vcc
	v_add_co_u32_e32 v34, vcc, s42, v214
	global_load_dwordx4 v[30:33], v[30:31], off
	s_nop 0
	v_addc_co_u32_e32 v35, vcc, 0, v215, vcc
	v_add_co_u32_e32 v42, vcc, s41, v216
	global_load_dwordx4 v[34:37], v[34:35], off
	s_nop 0
	v_addc_co_u32_e32 v43, vcc, 0, v217, vcc
	v_add_co_u32_e32 v46, vcc, s42, v216
	global_load_dwordx4 v[42:45], v[42:43], off
	s_nop 0
	v_addc_co_u32_e32 v47, vcc, 0, v217, vcc
	v_add_co_u32_e32 v50, vcc, s41, v218
	global_load_dwordx4 v[46:49], v[46:47], off
	s_nop 0
	v_addc_co_u32_e32 v51, vcc, 0, v219, vcc
	v_add_co_u32_e32 v54, vcc, s42, v218
	global_load_dwordx4 v[50:53], v[50:51], off
	s_nop 0
	v_addc_co_u32_e32 v55, vcc, 0, v219, vcc
	v_add_co_u32_e32 v58, vcc, s41, v220
	global_load_dwordx4 v[54:57], v[54:55], off
	s_nop 0
	v_addc_co_u32_e32 v59, vcc, 0, v221, vcc
	v_add_co_u32_e32 v62, vcc, s42, v220
	global_load_dwordx4 v[58:61], v[58:59], off
	s_nop 0
	v_addc_co_u32_e32 v63, vcc, 0, v221, vcc
	v_add_co_u32_e32 v130, vcc, s43, v222
	global_load_dwordx4 v[62:65], v[62:63], off
	s_nop 0
	v_addc_co_u32_e32 v131, vcc, 0, v223, vcc
	global_load_dword v245, v[130:131], off
	global_load_dword v246, v[130:131], off offset:256
	global_load_dword v247, v[130:131], off offset:512
	global_load_dword v248, v[130:131], off offset:768
	v_add_co_u32_e32 v130, vcc, s44, v224
	s_nop 1
	v_addc_co_u32_e32 v131, vcc, 0, v225, vcc
	v_add_co_u32_e32 v134, vcc, s44, v226
	global_load_dwordx4 v[130:133], v[130:131], off
	s_nop 0
	v_addc_co_u32_e32 v135, vcc, 0, v227, vcc
	v_add_co_u32_e32 v146, vcc, s45, v228
	global_load_dwordx4 v[138:141], v[134:135], off
	s_nop 0
	v_addc_co_u32_e32 v147, vcc, 0, v229, vcc
	v_add_co_u32_e32 v142, vcc, s45, v230
	global_load_dwordx4 v[134:137], v[146:147], off
	s_nop 0
	v_addc_co_u32_e32 v143, vcc, 0, v231, vcc
	global_load_dwordx4 v[142:145], v[142:143], off
	s_nop 0
	global_load_dwordx4 v[146:149], v[146:147], off offset:1024

	s_waitcnt lgkmcnt(0)
	v_mfma_f32_16x16x32_bf16 v[98:101], v[98:101], v[154:157], 0
	v_add_co_u32_e32 v150, vcc, s45, v232
	v_mfma_f32_16x16x32_bf16 v[102:105], v[102:105], v[154:157], 0
	ds_read_b128 v[154:157], v237 offset:64
	v_addc_co_u32_e32 v151, vcc, 0, v233, vcc
	s_waitcnt lgkmcnt(0)
	v_mfma_f32_16x16x32_bf16 v[98:101], v[106:109], v[154:157], v[98:101]
	ds_read_b128 v[106:109], v237 offset:128
	global_load_dwordx4 v[150:153], v[150:151], off
	v_mfma_f32_16x16x32_bf16 v[102:105], v[110:113], v[154:157], v[102:105]
	s_waitcnt lgkmcnt(0)
	v_mfma_f32_16x16x32_bf16 v[98:101], v[114:117], v[106:109], v[98:101]
	v_mfma_f32_16x16x32_bf16 v[102:105], v[118:121], v[106:109], v[102:105]
	ds_read_b128 v[106:109], v237 offset:192
	s_waitcnt lgkmcnt(0)
	v_mfma_f32_16x16x32_bf16 v[98:101], v[122:125], v[106:109], v[98:101]
	v_mfma_f32_16x16x32_bf16 v[102:105], v[126:129], v[106:109], v[102:105]
	s_nop 6
	v_sub_f32_e32 v101, v244, v101
	v_sub_f32_e32 v100, v243, v100
	v_sub_f32_e32 v99, v242, v99
	v_sub_f32_e32 v98, v241, v98
	v_cvt_pk_bf16_f32 v98, v98, v99
	v_cvt_pk_bf16_f32 v99, v100, v101
	ds_write_b64 v236, v[98:99] offset:4352
	s_waitcnt lgkmcnt(0)
	s_barrier
	ds_read_b128 v[98:101], v235 offset:4352
	ds_read_b128 v[106:109], v235 offset:4416
	s_waitcnt vmcnt(27) lgkmcnt(1)
	v_mfma_f32_16x16x32_bf16 v[66:69], v[66:69], v[98:101], v[102:105]
	s_waitcnt vmcnt(26) lgkmcnt(0)
	v_mfma_f32_16x16x32_bf16 v[66:69], v[74:77], v[106:109], v[66:69]
	v_mul_f32_e64 v76, v92, s66
	v_mul_f32_e64 v77, v93, s66
	v_pk_mul_f32 v[74:75], v[90:91], s[66:67] op_sel_hi:[1,0]
	v_pk_mul_f32 v[92:93], v[96:97], s[66:67] op_sel_hi:[1,0]
	v_pk_mul_f32 v[90:91], v[94:95], s[66:67] op_sel_hi:[1,0]
	s_waitcnt vmcnt(25)
	v_mfma_f32_16x16x32_bf16 v[70:73], v[70:73], v[98:101], v[74:77]
	s_waitcnt vmcnt(24)
	v_mfma_f32_16x16x32_bf16 v[122:125], v[78:81], v[106:109], v[70:73]
	s_waitcnt vmcnt(23)
	v_mfma_f32_16x16x32_bf16 v[70:73], v[82:85], v[98:101], v[90:93]
	s_waitcnt vmcnt(22)
	v_mfma_f32_16x16x32_bf16 v[126:129], v[86:89], v[106:109], v[70:73]
	s_nop 5
	v_cvt_pk_bf16_f32 v70, v122, v123
	v_cvt_pk_bf16_f32 v71, v124, v125
	v_cvt_pk_bf16_f32 v72, v126, v127
	v_cvt_pk_bf16_f32 v73, v128, v129
	ds_write2_b64 v234, v[70:71], v[72:73] offset1:4
	v_add_u32_e32 v70, 0x80, v192
	v_ashrrev_i32_e32 v71, 31, v70
	v_lshlrev_b64 v[70:71], 12, v[70:71]
	v_lshl_add_u64 v[70:71], v[190:191], 0, v[70:71]
	v_add_co_u32_e32 v72, vcc, s30, v70
	global_store_dword v[70:71], v66, off
	s_nop 0
	v_addc_co_u32_e32 v73, vcc, 0, v71, vcc
	v_add_co_u32_e32 v66, vcc, s31, v70
	global_store_dword v[72:73], v67, off offset:-4096
	global_store_dword v[72:73], v68, off
	v_addc_co_u32_e32 v67, vcc, 0, v71, vcc
	global_store_dword v[66:67], v69, off
	v_add_co_u32_e32 v66, vcc, s46, v214
	s_waitcnt lgkmcnt(0)
	s_barrier
	ds_read_b128 v[154:157], v237
	s_nop 0
	v_addc_co_u32_e32 v67, vcc, 0, v215, vcc
	global_load_dwordx4 v[90:93], v[66:67], off
	v_add_co_u32_e32 v66, vcc, s47, v214
	s_nop 1
	v_addc_co_u32_e32 v67, vcc, 0, v215, vcc
	global_load_dwordx4 v[94:97], v[66:67], off
	v_add_co_u32_e32 v66, vcc, s46, v216
	s_nop 1
	v_addc_co_u32_e32 v67, vcc, 0, v217, vcc
	global_load_dwordx4 v[98:101], v[66:67], off
	v_add_co_u32_e32 v66, vcc, s47, v216
	s_nop 1
	v_addc_co_u32_e32 v67, vcc, 0, v217, vcc
	global_load_dwordx4 v[102:105], v[66:67], off
	v_add_co_u32_e32 v66, vcc, s46, v218
	s_nop 1
	v_addc_co_u32_e32 v67, vcc, 0, v219, vcc
	global_load_dwordx4 v[106:109], v[66:67], off
	v_add_co_u32_e32 v66, vcc, s47, v218
	s_nop 1
	v_addc_co_u32_e32 v67, vcc, 0, v219, vcc
	global_load_dwordx4 v[110:113], v[66:67], off
	v_add_co_u32_e32 v66, vcc, s46, v220
	s_nop 1
	v_addc_co_u32_e32 v67, vcc, 0, v221, vcc
	global_load_dwordx4 v[114:117], v[66:67], off
	v_add_co_u32_e32 v66, vcc, s47, v220
	s_nop 1
	v_addc_co_u32_e32 v67, vcc, 0, v221, vcc
	global_load_dwordx4 v[118:121], v[66:67], off
	v_add_co_u32_e32 v66, vcc, s48, v222
	s_nop 1
	v_addc_co_u32_e32 v67, vcc, 0, v223, vcc
	global_load_dword v241, v[66:67], off
	global_load_dword v242, v[66:67], off offset:256
	global_load_dword v243, v[66:67], off offset:512
	global_load_dword v244, v[66:67], off offset:768
	v_add_co_u32_e32 v66, vcc, s49, v224
	s_nop 1
	v_addc_co_u32_e32 v67, vcc, 0, v225, vcc
	v_add_co_u32_e32 v70, vcc, s49, v226
	global_load_dwordx4 v[66:69], v[66:67], off
	s_nop 0
	v_addc_co_u32_e32 v71, vcc, 0, v227, vcc
	v_add_co_u32_e32 v82, vcc, s50, v228
	global_load_dwordx4 v[74:77], v[70:71], off
	s_nop 0
	v_addc_co_u32_e32 v83, vcc, 0, v229, vcc
	v_add_co_u32_e32 v78, vcc, s50, v230
	global_load_dwordx4 v[70:73], v[82:83], off
	s_nop 0
	v_addc_co_u32_e32 v79, vcc, 0, v231, vcc
	global_load_dwordx4 v[78:81], v[78:79], off
	s_nop 0
	global_load_dwordx4 v[82:85], v[82:83], off offset:1024

	s_waitcnt lgkmcnt(0)
	v_mfma_f32_16x16x32_bf16 v[2:5], v[2:5], v[154:157], 0
	v_add_co_u32_e32 v86, vcc, s50, v232
	v_mfma_f32_16x16x32_bf16 v[6:9], v[6:9], v[154:157], 0
	ds_read_b128 v[154:157], v237 offset:64
	v_addc_co_u32_e32 v87, vcc, 0, v233, vcc
	s_waitcnt lgkmcnt(0)
	v_mfma_f32_16x16x32_bf16 v[2:5], v[10:13], v[154:157], v[2:5]
	ds_read_b128 v[10:13], v237 offset:128
	global_load_dwordx4 v[86:89], v[86:87], off
	v_mfma_f32_16x16x32_bf16 v[6:9], v[14:17], v[154:157], v[6:9]
	s_waitcnt lgkmcnt(0)
	v_mfma_f32_16x16x32_bf16 v[2:5], v[18:21], v[10:13], v[2:5]
	v_mul_f32_e64 v20, v128, s64
	v_mul_f32_e64 v21, v129, s64
	v_pk_mul_f32 v[18:19], v[126:127], s[64:65] op_sel_hi:[1,0]
	v_mfma_f32_16x16x32_bf16 v[6:9], v[22:25], v[10:13], v[6:9]
	ds_read_b128 v[10:13], v237 offset:192
	s_waitcnt lgkmcnt(0)
	v_mfma_f32_16x16x32_bf16 v[2:5], v[26:29], v[10:13], v[2:5]
	v_mfma_f32_16x16x32_bf16 v[6:9], v[38:41], v[10:13], v[6:9]
	s_nop 6
	v_sub_f32_e32 v5, v240, v5
	v_sub_f32_e32 v4, v239, v4
	v_sub_f32_e32 v3, v238, v3
	v_sub_f32_e32 v2, v193, v2
	v_cvt_pk_bf16_f32 v2, v2, v3
	v_cvt_pk_bf16_f32 v3, v4, v5
	ds_write_b64 v236, v[2:3] offset:4352
	s_waitcnt lgkmcnt(0)
	s_barrier
	ds_read_b128 v[10:13], v235 offset:4352
	ds_read_b128 v[14:17], v235 offset:4416
	s_waitcnt vmcnt(27) lgkmcnt(1)
	v_mfma_f32_16x16x32_bf16 v[2:5], v[130:133], v[10:13], v[6:9]
	s_nop 2
	v_mul_f32_e64 v8, v124, s64
	v_mul_f32_e64 v9, v125, s64
	v_pk_mul_f32 v[6:7], v[122:123], s[64:65] op_sel_hi:[1,0]
	v_readlane_b32 s64, v177, s65
	s_waitcnt vmcnt(26) lgkmcnt(0)
	v_mfma_f32_16x16x32_bf16 v[2:5], v[138:141], v[14:17], v[2:5]
	s_waitcnt vmcnt(25)
	v_mfma_f32_16x16x32_bf16 v[6:9], v[134:137], v[10:13], v[6:9]
	s_waitcnt vmcnt(24)
	v_mfma_f32_16x16x32_bf16 v[154:157], v[142:145], v[14:17], v[6:9]
	s_waitcnt vmcnt(23)
	v_mfma_f32_16x16x32_bf16 v[6:9], v[146:149], v[10:13], v[18:21]
	s_waitcnt vmcnt(22)
	v_mfma_f32_16x16x32_bf16 v[146:149], v[150:153], v[14:17], v[6:9]
	s_nop 5
	v_cvt_pk_bf16_f32 v6, v154, v155
	v_cvt_pk_bf16_f32 v7, v156, v157
	v_cvt_pk_bf16_f32 v8, v146, v147
	v_cvt_pk_bf16_f32 v9, v148, v149
	ds_write2_b64 v234, v[6:7], v[8:9] offset1:4
	v_add_u32_e32 v6, 0xc0, v192
	v_ashrrev_i32_e32 v7, 31, v6
	v_lshlrev_b64 v[6:7], 12, v[6:7]
	v_lshl_add_u64 v[6:7], v[190:191], 0, v[6:7]
	v_add_co_u32_e32 v8, vcc, s30, v6
	global_store_dword v[6:7], v2, off
	s_nop 0
	v_addc_co_u32_e32 v9, vcc, 0, v7, vcc
	v_add_co_u32_e32 v2, vcc, s31, v6
	global_store_dword v[8:9], v3, off offset:-4096
	global_store_dword v[8:9], v4, off
	v_addc_co_u32_e32 v3, vcc, 0, v7, vcc
	global_store_dword v[2:3], v5, off
	v_add_co_u32_e32 v2, vcc, s51, v214
	s_waitcnt lgkmcnt(0)
	s_barrier
	ds_read_b128 v[150:153], v237
	s_nop 0
	v_addc_co_u32_e32 v3, vcc, 0, v215, vcc
	global_load_dwordx4 v[18:21], v[2:3], off
	v_add_co_u32_e32 v2, vcc, s52, v214
	s_nop 1
	v_addc_co_u32_e32 v3, vcc, 0, v215, vcc
	global_load_dwordx4 v[38:41], v[2:3], off
	v_add_co_u32_e32 v2, vcc, s51, v216
	s_nop 1
	v_addc_co_u32_e32 v3, vcc, 0, v217, vcc
	global_load_dwordx4 v[6:9], v[2:3], off
	v_add_co_u32_e32 v2, vcc, s52, v216
	s_nop 1
	v_addc_co_u32_e32 v3, vcc, 0, v217, vcc
	v_add_co_u32_e32 v10, vcc, s51, v218
	global_load_dwordx4 v[2:5], v[2:3], off
	s_nop 0
	v_addc_co_u32_e32 v11, vcc, 0, v219, vcc
	global_load_dwordx4 v[26:29], v[10:11], off
	v_add_co_u32_e32 v10, vcc, s52, v218
	s_nop 1
	v_addc_co_u32_e32 v11, vcc, 0, v219, vcc
	global_load_dwordx4 v[14:17], v[10:11], off
	v_add_co_u32_e32 v10, vcc, s51, v220
	s_nop 1
	v_addc_co_u32_e32 v11, vcc, 0, v221, vcc
	global_load_dwordx4 v[22:25], v[10:11], off
	v_add_co_u32_e32 v10, vcc, s52, v220
	s_nop 1
	v_addc_co_u32_e32 v11, vcc, 0, v221, vcc
	v_add_co_u32_e32 v122, vcc, s53, v222
	global_load_dwordx4 v[10:13], v[10:11], off
	s_nop 0
	v_addc_co_u32_e32 v123, vcc, 0, v223, vcc
	global_load_dword v193, v[122:123], off
	global_load_dword v238, v[122:123], off offset:256
	global_load_dword v239, v[122:123], off offset:512
	global_load_dword v240, v[122:123], off offset:768
	v_add_co_u32_e32 v122, vcc, s54, v224
	s_nop 1
	v_addc_co_u32_e32 v123, vcc, 0, v225, vcc
	v_add_co_u32_e32 v126, vcc, s54, v226
	global_load_dwordx4 v[122:125], v[122:123], off
	s_nop 0
	v_addc_co_u32_e32 v127, vcc, 0, v227, vcc
	v_add_co_u32_e32 v138, vcc, s55, v228
	global_load_dwordx4 v[130:133], v[126:127], off
	s_nop 0
	v_addc_co_u32_e32 v139, vcc, 0, v229, vcc
	v_add_co_u32_e32 v134, vcc, s55, v230
	global_load_dwordx4 v[126:129], v[138:139], off
	s_nop 0
	v_addc_co_u32_e32 v135, vcc, 0, v231, vcc
	global_load_dwordx4 v[134:137], v[134:135], off
	s_nop 0
	global_load_dwordx4 v[138:141], v[138:139], off offset:1024

	s_waitcnt lgkmcnt(0)
	v_mfma_f32_16x16x32_bf16 v[30:33], v[30:33], v[150:153], 0
	v_add_co_u32_e32 v142, vcc, s55, v232
	v_mfma_f32_16x16x32_bf16 v[34:37], v[34:37], v[150:153], 0
	ds_read_b128 v[150:153], v237 offset:64
	v_addc_co_u32_e32 v143, vcc, 0, v233, vcc
	s_waitcnt lgkmcnt(0)
	v_mfma_f32_16x16x32_bf16 v[30:33], v[42:45], v[150:153], v[30:33]
	ds_read_b128 v[42:45], v237 offset:128
	global_load_dwordx4 v[142:145], v[142:143], off
	v_mfma_f32_16x16x32_bf16 v[34:37], v[46:49], v[150:153], v[34:37]
	s_waitcnt lgkmcnt(0)
	v_mfma_f32_16x16x32_bf16 v[30:33], v[50:53], v[42:45], v[30:33]
	v_mul_f32_e64 v52, v148, s64
	v_mul_f32_e64 v53, v149, s64
	v_pk_mul_f32 v[50:51], v[146:147], s[64:65] op_sel_hi:[1,0]
	v_mfma_f32_16x16x32_bf16 v[34:37], v[54:57], v[42:45], v[34:37]
	ds_read_b128 v[42:45], v237 offset:192
	s_waitcnt lgkmcnt(0)
	v_mfma_f32_16x16x32_bf16 v[30:33], v[58:61], v[42:45], v[30:33]
	v_mfma_f32_16x16x32_bf16 v[34:37], v[62:65], v[42:45], v[34:37]
	s_nop 6
	v_sub_f32_e32 v33, v248, v33
	v_sub_f32_e32 v32, v247, v32
	v_sub_f32_e32 v31, v246, v31
	v_sub_f32_e32 v30, v245, v30
	v_cvt_pk_bf16_f32 v30, v30, v31
	v_cvt_pk_bf16_f32 v31, v32, v33
	ds_write_b64 v236, v[30:31] offset:4352
	s_waitcnt lgkmcnt(0)
	s_barrier
	ds_read_b128 v[42:45], v235 offset:4352
	ds_read_b128 v[46:49], v235 offset:4416
	s_waitcnt vmcnt(27) lgkmcnt(1)
	v_mfma_f32_16x16x32_bf16 v[30:33], v[66:69], v[42:45], v[34:37]
	s_nop 2
	v_mul_f32_e64 v36, v156, s64
	v_mul_f32_e64 v37, v157, s64
	v_pk_mul_f32 v[34:35], v[154:155], s[64:65] op_sel_hi:[1,0]
	s_waitcnt vmcnt(26) lgkmcnt(0)
	v_mfma_f32_16x16x32_bf16 v[30:33], v[74:77], v[46:49], v[30:33]
	s_waitcnt vmcnt(25)
	v_mfma_f32_16x16x32_bf16 v[34:37], v[70:73], v[42:45], v[34:37]
	s_waitcnt vmcnt(24)
	v_mfma_f32_16x16x32_bf16 v[146:149], v[78:81], v[46:49], v[34:37]
	s_waitcnt vmcnt(23)
	v_mfma_f32_16x16x32_bf16 v[34:37], v[82:85], v[42:45], v[50:53]
	s_waitcnt vmcnt(22)
	v_mfma_f32_16x16x32_bf16 v[150:153], v[86:89], v[46:49], v[34:37]
	s_nop 5
	v_cvt_pk_bf16_f32 v34, v146, v147
	v_cvt_pk_bf16_f32 v35, v148, v149
	v_cvt_pk_bf16_f32 v36, v150, v151
	v_cvt_pk_bf16_f32 v37, v152, v153
	ds_write2_b64 v234, v[34:35], v[36:37] offset1:4
	v_add_u32_e32 v34, 0x100, v192
	v_ashrrev_i32_e32 v35, 31, v34
	v_lshlrev_b64 v[34:35], 12, v[34:35]
	v_lshl_add_u64 v[34:35], v[190:191], 0, v[34:35]
	v_add_co_u32_e32 v36, vcc, s30, v34
	global_store_dword v[34:35], v30, off
	s_nop 0
	v_addc_co_u32_e32 v37, vcc, 0, v35, vcc
	v_add_co_u32_e32 v30, vcc, s31, v34
	global_store_dword v[36:37], v31, off offset:-4096
	global_store_dword v[36:37], v32, off
	v_addc_co_u32_e32 v31, vcc, 0, v35, vcc
	global_store_dword v[30:31], v33, off
	v_add_co_u32_e32 v30, vcc, s56, v214
	s_waitcnt lgkmcnt(0)
	s_barrier
	s_nop 0
	v_addc_co_u32_e32 v31, vcc, 0, v215, vcc
	v_add_co_u32_e32 v34, vcc, s57, v214
	global_load_dwordx4 v[30:33], v[30:31], off
	s_nop 0
	v_addc_co_u32_e32 v35, vcc, 0, v215, vcc
	v_add_co_u32_e32 v42, vcc, s56, v216
	global_load_dwordx4 v[34:37], v[34:35], off
	s_nop 0
	v_addc_co_u32_e32 v43, vcc, 0, v217, vcc
	global_load_dwordx4 v[46:49], v[42:43], off
	v_add_co_u32_e32 v42, vcc, s57, v216
	s_nop 1
	v_addc_co_u32_e32 v43, vcc, 0, v217, vcc
	ds_read_b128 v[214:217], v237
	global_load_dwordx4 v[50:53], v[42:43], off
	v_add_co_u32_e32 v42, vcc, s56, v218
	s_nop 1
	v_addc_co_u32_e32 v43, vcc, 0, v219, vcc
	v_add_co_u32_e32 v54, vcc, s57, v218
	global_load_dwordx4 v[42:45], v[42:43], off
	s_nop 0
	v_addc_co_u32_e32 v55, vcc, 0, v219, vcc
	v_add_co_u32_e32 v58, vcc, s56, v220
	global_load_dwordx4 v[54:57], v[54:55], off
	s_nop 0
	v_addc_co_u32_e32 v59, vcc, 0, v221, vcc
	v_add_co_u32_e32 v62, vcc, s57, v220
	global_load_dwordx4 v[58:61], v[58:59], off
	s_nop 0
	v_addc_co_u32_e32 v63, vcc, 0, v221, vcc
	v_add_co_u32_e32 v66, vcc, s58, v222
	global_load_dwordx4 v[62:65], v[62:63], off
	s_nop 0
	v_addc_co_u32_e32 v67, vcc, 0, v223, vcc
	global_load_dword v157, v[66:67], off
	global_load_dword v154, v[66:67], off offset:256
	global_load_dword v155, v[66:67], off offset:512
	global_load_dword v156, v[66:67], off offset:768
	v_add_co_u32_e32 v66, vcc, s59, v224
	s_nop 1
	v_addc_co_u32_e32 v67, vcc, 0, v225, vcc
	global_load_dwordx4 v[86:89], v[66:67], off
	v_add_co_u32_e32 v66, vcc, s59, v226
	s_nop 1
	v_addc_co_u32_e32 v67, vcc, 0, v227, vcc
	global_load_dwordx4 v[74:77], v[66:67], off
	v_add_co_u32_e32 v66, vcc, s60, v228
	s_nop 1
	v_addc_co_u32_e32 v67, vcc, 0, v229, vcc
	v_add_co_u32_e32 v68, vcc, s60, v230
	global_load_dwordx4 v[70:73], v[66:67], off
	s_nop 0
	v_addc_co_u32_e32 v69, vcc, 0, v231, vcc
	v_add_co_u32_e32 v78, vcc, s60, v232
	global_load_dwordx4 v[82:85], v[68:69], off
	s_nop 0
	global_load_dwordx4 v[66:69], v[66:67], off offset:1024
	v_addc_co_u32_e32 v79, vcc, 0, v233, vcc
	global_load_dwordx4 v[78:81], v[78:79], off

; DEV void gdn_scan_item(const Params& p, int item, unsigned char* lds) {
;     ...
;     LOAD_E(E0, 0); LOAD_L(L0, 0); LOAD_E(E1, 1);
;     __syncthreads();
;     for (int ch = 0; ch < 30; ch += 6) {
;         SCAN_STEP(E0, E2, L0, L1, ch);     SCAN_STEP(E1, E0, L1, L0, ch + 1); SCAN_STEP(E2, E1, L0, L1, ch + 2);
;         SCAN_STEP(E0, E2, L1, L0, ch + 3); SCAN_STEP(E1, E0, L0, L1, ch + 4); SCAN_STEP(E2, E1, L1, L0, ch + 5);
;     }
;     SCAN_STEP(E0, E2, L0, L1, 30); SCAN_STEP(E1, E0, L1, L0, 31);
	s_waitcnt lgkmcnt(0)
	v_mfma_f32_16x16x32_bf16 v[90:93], v[90:93], v[214:217], 0
	v_mfma_f32_16x16x32_bf16 v[94:97], v[94:97], v[214:217], 0
	ds_read_b128 v[214:217], v237 offset:64
	s_waitcnt lgkmcnt(0)
	v_mfma_f32_16x16x32_bf16 v[90:93], v[98:101], v[214:217], v[90:93]
	ds_read_b128 v[98:101], v237 offset:128
	v_mfma_f32_16x16x32_bf16 v[94:97], v[102:105], v[214:217], v[94:97]
	s_waitcnt lgkmcnt(0)
	v_mfma_f32_16x16x32_bf16 v[90:93], v[106:109], v[98:101], v[90:93]
	v_mul_f32_e64 v108, v152, s62
	v_mul_f32_e64 v109, v153, s62
	v_pk_mul_f32 v[106:107], v[150:151], s[62:63] op_sel_hi:[1,0]
	v_mfma_f32_16x16x32_bf16 v[94:97], v[110:113], v[98:101], v[94:97]
	ds_read_b128 v[98:101], v237 offset:192
	s_waitcnt lgkmcnt(0)
	v_mfma_f32_16x16x32_bf16 v[90:93], v[114:117], v[98:101], v[90:93]
	v_mfma_f32_16x16x32_bf16 v[94:97], v[118:121], v[98:101], v[94:97]
	s_nop 6
	v_sub_f32_e32 v93, v244, v93
	v_sub_f32_e32 v92, v243, v92
	v_sub_f32_e32 v91, v242, v91
	v_sub_f32_e32 v90, v241, v90
	v_cvt_pk_bf16_f32 v90, v90, v91
	v_cvt_pk_bf16_f32 v91, v92, v93
	ds_write_b64 v236, v[90:91] offset:4352
	s_waitcnt lgkmcnt(0)
	s_barrier
	ds_read_b128 v[90:93], v235 offset:4352
	ds_read_b128 v[102:105], v235 offset:4416
	s_waitcnt vmcnt(27) lgkmcnt(1)
	v_mfma_f32_16x16x32_bf16 v[94:97], v[122:125], v[90:93], v[94:97]
	s_waitcnt vmcnt(26) lgkmcnt(0)
	v_mfma_f32_16x16x32_bf16 v[98:101], v[130:133], v[102:105], v[94:97]
	s_nop 5
	v_mul_f32_e64 v96, v148, s62
	v_mul_f32_e64 v97, v149, s62
	v_pk_mul_f32 v[94:95], v[146:147], s[62:63] op_sel_hi:[1,0]
	s_mov_b32 s62, s61
	s_waitcnt vmcnt(25)
	v_mfma_f32_16x16x32_bf16 v[94:97], v[126:129], v[90:93], v[94:97]
	s_waitcnt vmcnt(23)
	v_mfma_f32_16x16x32_bf16 v[90:93], v[138:141], v[90:93], v[106:109]
	v_mfma_f32_16x16x32_bf16 v[94:97], v[134:137], v[102:105], v[94:97]
	s_waitcnt vmcnt(22)
	v_mfma_f32_16x16x32_bf16 v[90:93], v[142:145], v[102:105], v[90:93]
	s_nop 5
	v_cvt_pk_bf16_f32 v102, v94, v95
	v_cvt_pk_bf16_f32 v103, v96, v97
	v_cvt_pk_bf16_f32 v104, v90, v91
	v_cvt_pk_bf16_f32 v105, v92, v93
	ds_write2_b64 v234, v[102:103], v[104:105] offset1:4
	v_add_u32_e32 v102, 0x140, v192
	v_ashrrev_i32_e32 v103, 31, v102
	v_lshlrev_b64 v[102:103], 12, v[102:103]
	v_lshl_add_u64 v[102:103], v[190:191], 0, v[102:103]
	v_add_co_u32_e32 v104, vcc, s30, v102
	global_store_dword v[102:103], v98, off
	s_nop 0
	v_addc_co_u32_e32 v105, vcc, 0, v103, vcc
	v_add_co_u32_e32 v98, vcc, s31, v102
	global_store_dword v[104:105], v99, off offset:-4096
	global_store_dword v[104:105], v100, off
	v_addc_co_u32_e32 v99, vcc, 0, v103, vcc
	global_store_dword v[98:99], v101, off
	s_waitcnt lgkmcnt(0)
	s_barrier
	v_add_u32_e32 v192, 0x180, v192
	s_cbranch_scc1 .LBB0_888
	ds_read_b128 v[98:101], v237
	ds_read_b128 v[102:105], v237 offset:64
	s_add_u32 s8, s12, 0x3e000
	s_addc_u32 s9, s13, 0
	v_lshl_add_u64 v[106:107], s[8:9], 0, v[180:181]
	s_waitcnt lgkmcnt(1)
	v_mfma_f32_16x16x32_bf16 v[18:21], v[18:21], v[98:101], 0
	v_or_b32_e32 v108, 0x400, v184
	v_add3_u32 v1, v1, s24, v179
	s_movk_i32 s13, 0x2000
	v_mfma_f32_16x16x32_bf16 v[38:41], v[38:41], v[98:101], 0
	v_lshl_add_u64 v[98:99], s[8:9], 0, v[182:183]
	s_add_u32 s8, s10, 0x7c000
	s_addc_u32 s9, s11, 0
	s_waitcnt lgkmcnt(0)
	v_mfma_f32_16x16x32_bf16 v[6:9], v[6:9], v[102:105], v[18:21]
	v_lshl_add_u64 v[100:101], s[8:9], 0, v[184:185]
	v_lshl_add_u64 v[110:111], s[8:9], 0, v[188:189]
	s_lshl_b32 s10, s23, 2
	ds_read_b128 v[18:21], v237 offset:128
	v_mfma_f32_16x16x32_bf16 v[2:5], v[2:5], v[102:105], v[38:41]
	s_nop 2
	global_load_dwordx4 v[38:41], v[98:99], off
	s_nop 0
	global_load_dwordx4 v[98:101], v[100:101], off
	ds_read_b128 v[102:105], v237 offset:192
	s_movk_i32 s16, 0x3000
	s_waitcnt lgkmcnt(1)
	v_mfma_f32_16x16x32_bf16 v[6:9], v[26:29], v[18:21], v[6:9]
	global_load_dwordx4 v[26:29], v[106:107], off
	s_nop 0
	global_load_dwordx4 v[106:109], v108, s[8:9]
	v_readlane_b32 s12, v177, 31
	s_lshl_b64 s[4:5], s[4:5], 7
	v_mfma_f32_16x16x32_bf16 v[2:5], v[14:17], v[18:21], v[2:5]
	v_lshl_add_u64 v[18:19], s[8:9], 0, v[186:187]
	global_load_dwordx4 v[14:17], v[110:111], off
	s_nop 0
	global_load_dwordx4 v[18:21], v[18:19], off
	v_readlane_b32 s8, v177, 30
	s_waitcnt lgkmcnt(0)
	v_mfma_f32_16x16x32_bf16 v[6:9], v[22:25], v[102:105], v[6:9]
	v_ashrrev_i32_e32 v177, 31, v176
	v_pk_mul_f32 v[24:25], v[96:97], s[8:9] op_sel_hi:[1,0]
	v_pk_mul_f32 v[22:23], v[94:95], s[8:9] op_sel_hi:[1,0]
	v_mfma_f32_16x16x32_bf16 v[2:5], v[10:13], v[102:105], v[2:5]
	s_nop 3
	v_sub_f32_e32 v9, v240, v9
	v_sub_f32_e32 v8, v239, v8
	v_sub_f32_e32 v7, v238, v7
	v_sub_f32_e32 v6, v193, v6
	v_cvt_pk_bf16_f32 v6, v6, v7
	v_cvt_pk_bf16_f32 v7, v8, v9
	ds_write_b64 v236, v[6:7] offset:4352
	s_waitcnt lgkmcnt(0)
	s_barrier
; DEV void gdn_scan_item(const Params& p, int item, unsigned char* lds) {
;     ...
;     LOAD_E(E0, 0); LOAD_L(L0, 0); LOAD_E(E1, 1);
;     __syncthreads();
;     for (int ch = 0; ch < 30; ch += 6) {
;         SCAN_STEP(E0, E2, L0, L1, ch);     SCAN_STEP(E1, E0, L1, L0, ch + 1); SCAN_STEP(E2, E1, L0, L1, ch + 2);
;         SCAN_STEP(E0, E2, L1, L0, ch + 3); SCAN_STEP(E1, E0, L0, L1, ch + 4); SCAN_STEP(E2, E1, L1, L0, ch + 5);
;     }
;     SCAN_STEP(E0, E2, L0, L1, 30); SCAN_STEP(E1, E0, L1, L0, 31);
;     ...
;     {
;         float* dp = p.out + O_DP + ((size_t)bh * 128 + w * 32 + fq * 4) * 128 + s * 16 + fr;
; #pragma unroll
;         for (int e = 0; e < 4; ++e) { dp[e * 128] = S0[e]; dp[(16 + e) * 128] = S1[e]; }
;     }
;     __syncthreads();
	ds_read_b128 v[6:9], v235 offset:4352
	ds_read_b128 v[10:13], v235 offset:4416
	s_waitcnt vmcnt(13) lgkmcnt(1)
	v_mfma_f32_16x16x32_bf16 v[22:25], v[70:73], v[6:9], v[22:25]
	v_mul_f32_e64 v72, v92, s8
	v_mul_f32_e64 v73, v93, s8
	v_pk_mul_f32 v[70:71], v[90:91], s[8:9] op_sel_hi:[1,0]
	s_mov_b32 s9, 0
	v_mfma_f32_16x16x32_bf16 v[2:5], v[86:89], v[6:9], v[2:5]
	s_lshl_b32 s8, s22, 2
	s_mov_b32 s11, s9
	s_waitcnt vmcnt(11)
	v_mfma_f32_16x16x32_bf16 v[6:9], v[66:69], v[6:9], v[70:73]
	s_waitcnt lgkmcnt(0)
	v_mfma_f32_16x16x32_bf16 v[22:25], v[82:85], v[10:13], v[22:25]
	s_waitcnt vmcnt(10)
	v_mfma_f32_16x16x32_bf16 v[6:9], v[78:81], v[10:13], v[6:9]
	v_mfma_f32_16x16x32_bf16 v[2:5], v[74:77], v[10:13], v[2:5]
	v_add_u32_e32 v10, 0x780, v1
	v_ashrrev_i32_e32 v11, 31, v10
	v_lshlrev_b64 v[10:11], 12, v[10:11]
	v_lshl_add_u64 v[10:11], s[6:7], 0, v[10:11]
	s_nop 0
	v_cvt_pk_bf16_f32 v66, v22, v23
	v_cvt_pk_bf16_f32 v67, v24, v25
	v_cvt_pk_bf16_f32 v68, v6, v7
	v_cvt_pk_bf16_f32 v69, v8, v9
	v_lshl_add_u64 v[10:11], v[10:11], 0, s[8:9]
	ds_write2_b64 v234, v[66:67], v[68:69] offset1:4
	v_lshl_add_u64 v[10:11], v[10:11], 0, s[10:11]
	v_lshlrev_b32_e32 v66, 2, v178
	v_mov_b32_e32 v67, 0
	v_lshl_add_u64 v[10:11], v[10:11], 0, v[66:67]
	v_add_co_u32_e32 v12, vcc, s13, v10
	global_store_dword v[10:11], v2, off
	s_nop 0
	v_addc_co_u32_e32 v13, vcc, 0, v11, vcc
	v_add_co_u32_e32 v2, vcc, s16, v10
	global_store_dword v[12:13], v3, off offset:-4096
	global_store_dword v[12:13], v4, off
	v_addc_co_u32_e32 v3, vcc, 0, v11, vcc
	global_store_dword v[2:3], v5, off
	s_waitcnt lgkmcnt(0)
	s_barrier
	ds_read_b128 v[2:5], v237
	ds_read_b128 v[10:13], v237 offset:64
	s_waitcnt lgkmcnt(1)
	v_mfma_f32_16x16x32_bf16 v[30:33], v[30:33], v[2:5], 0
	v_mul_f32_e64 v24, v24, s12
	v_mul_f32_e64 v25, v25, s12
	v_pk_mul_f32 v[22:23], v[22:23], s[12:13] op_sel_hi:[1,0]
	v_pk_mul_f32 v[8:9], v[8:9], s[12:13] op_sel_hi:[1,0]
	v_mfma_f32_16x16x32_bf16 v[2:5], v[34:37], v[2:5], 0
	v_mul_f32_e64 v6, v6, s12
	v_mul_f32_e64 v7, v7, s12
	s_waitcnt lgkmcnt(0)
	v_mfma_f32_16x16x32_bf16 v[30:33], v[46:49], v[10:13], v[30:33]
	v_mfma_f32_16x16x32_bf16 v[2:5], v[50:53], v[10:13], v[2:5]
	ds_read_b128 v[10:13], v237 offset:128
	ds_read_b128 v[34:37], v237 offset:192
	s_waitcnt lgkmcnt(1)
	v_mfma_f32_16x16x32_bf16 v[30:33], v[42:45], v[10:13], v[30:33]
	v_mfma_f32_16x16x32_bf16 v[2:5], v[54:57], v[10:13], v[2:5]
	s_waitcnt lgkmcnt(0)
	v_mfma_f32_16x16x32_bf16 v[10:13], v[58:61], v[34:37], v[30:33]
	v_mfma_f32_16x16x32_bf16 v[2:5], v[62:65], v[34:37], v[2:5]
	s_nop 6
	v_sub_f32_e32 v13, v156, v13
	v_sub_f32_e32 v12, v155, v12
	v_sub_f32_e32 v11, v154, v11
	v_sub_f32_e32 v10, v157, v10
	v_cvt_pk_bf16_f32 v10, v10, v11
	v_cvt_pk_bf16_f32 v11, v12, v13
	ds_write_b64 v236, v[10:11] offset:4352
	s_waitcnt lgkmcnt(0)
	s_barrier
	ds_read_b128 v[10:13], v235 offset:4352
	ds_read_b128 v[30:33], v235 offset:4416
	s_waitcnt vmcnt(8) lgkmcnt(1)
	v_mfma_f32_16x16x32_bf16 v[22:25], v[98:101], v[10:13], v[22:25]
	s_waitcnt vmcnt(6)
	v_mfma_f32_16x16x32_bf16 v[6:9], v[106:109], v[10:13], v[6:9]
	s_waitcnt vmcnt(5) lgkmcnt(0)
	v_mfma_f32_16x16x32_bf16 v[14:17], v[14:17], v[30:33], v[22:25]
	s_waitcnt vmcnt(4)
	v_mfma_f32_16x16x32_bf16 v[6:9], v[18:21], v[30:33], v[6:9]
	v_mfma_f32_16x16x32_bf16 v[2:5], v[26:29], v[10:13], v[2:5]
	s_nop 4
	v_cvt_pk_bf16_f32 v10, v14, v15
	v_cvt_pk_bf16_f32 v11, v16, v17
	v_cvt_pk_bf16_f32 v12, v6, v7
	v_cvt_pk_bf16_f32 v13, v8, v9
	ds_write2_b64 v234, v[10:11], v[12:13] offset1:4
	v_add_u32_e32 v10, 0x7c0, v1
	v_ashrrev_i32_e32 v11, 31, v10
	v_lshlrev_b64 v[10:11], 12, v[10:11]
	v_lshl_add_u64 v[10:11], s[6:7], 0, v[10:11]
	v_lshl_add_u64 v[10:11], v[10:11], 0, s[8:9]
	v_mfma_f32_16x16x32_bf16 v[2:5], v[38:41], v[30:33], v[2:5]
	v_lshl_add_u64 v[10:11], v[10:11], 0, s[10:11]
	v_lshl_add_u64 v[10:11], v[10:11], 0, v[66:67]
	v_add_co_u32_e32 v12, vcc, s13, v10
	s_nop 1
	v_addc_co_u32_e32 v13, vcc, 0, v11, vcc
	s_nop 1
	global_store_dword v[10:11], v2, off
	v_add_co_u32_e32 v2, vcc, s16, v10
	global_store_dword v[12:13], v3, off offset:-4096
	global_store_dword v[12:13], v4, off
	v_addc_co_u32_e32 v3, vcc, 0, v11, vcc
	global_store_dword v[2:3], v5, off
	s_waitcnt lgkmcnt(0)
	s_barrier
	s_load_dwordx2 s[6:7], s[0:1], 0xc0
	v_lshl_add_u64 v[2:3], s[4:5], 0, v[176:177]
	v_or_b32_e32 v2, v2, v179
	v_lshlrev_b64 v[2:3], 9, v[2:3]
	s_mov_b64 s[4:5], 0x5400000
	s_waitcnt lgkmcnt(0)
	v_lshl_add_u64 v[2:3], s[6:7], 0, v[2:3]
	v_lshl_add_u64 v[2:3], v[2:3], 0, s[10:11]
	v_lshl_add_u64 v[2:3], v[2:3], 0, v[66:67]
	v_lshl_add_u64 v[4:5], v[2:3], 0, s[4:5]
	s_mov_b32 s4, 0x5400000
	v_add_co_u32_e32 v10, vcc, s4, v2
	s_nop 1
	v_addc_co_u32_e32 v11, vcc, 0, v3, vcc
	v_add_co_u32_e32 v2, vcc, 0x5402000, v2
	global_store_dword v[10:11], v14, off
	s_nop 0
	v_addc_co_u32_e32 v3, vcc, 0, v3, vcc
	global_store_dword v[2:3], v6, off
	global_store_dword v[4:5], v15, off offset:512
	global_store_dword v[2:3], v7, off offset:512
	global_store_dword v[4:5], v16, off offset:1024
	global_store_dword v[2:3], v8, off offset:1024
	global_store_dword v[4:5], v17, off offset:1536
	global_store_dword v[2:3], v9, off offset:1536
	s_cmp_lg_u32 s71, 0
	s_cbranch_scc1 .Lscan_stag1
	s_barrier
.Lscan_stag1:
	s_barrier
